# nt on the final f32 output stores (written once, never read by the kernel)
# speedup vs baseline: 1.0069x; 1.0069x over previous
; __device__ __forceinline__ float bf_lo(unsigned w) { return __uint_as_float(w << 16); }
; __device__ __forceinline__ float bf_hi(unsigned w) { return __uint_as_float(w & 0xffff0000u); }
;     __device__ __forceinline__ void operator()(const f32x4 (&acc)[2][2][4][2], const Unit& u, int wr, int wc, int fr, int fq) const {
;     ...
;         if (MODE != 0) rstd8(rs8, xs_in, u.pm * 256 + wr * 64 + fr, 16, fq, 4, 1.0f / 1024.0f);
;         constexpr int NB = (MODE == 1) ? 2 : 4;
; #pragma unroll
;         for (int g = 0; g < 8 / NB; ++g) {
;             u32x4 xw[NB][2], pw[NB][2];
; #pragma unroll
;             for (int k = 0; k < NB; ++k)
; #pragma unroll
;                 for (int bj = 0; bj < 2; ++bj) {
;                     const int ai = (g * NB + k) >> 2, m = (g * NB + k) & 3;
;                     const size_t off = (size_t)(u.pm * 256 + ai * 128 + wr * 64 + m * 16 + fr) * 1024 + colb + bj * 128;
;                     xw[k][bj] = *(const u32x4*)(xold + off);
;                     if (MODE == 1) pw[k][bj] = *(const u32x4*)(pg + off);
;                 }
; #pragma unroll
;             for (int k = 0; k < NB; ++k) {
;                 const int ai = (g * NB + k) >> 2, m = (g * NB + k) & 3;
;                 const int row = u.pm * 256 + ai * 128 + wr * 64 + m * 16 + fr;
;                 float ss = 0.f;
; #pragma unroll
;                 for (int bj = 0; bj < 2; ++bj) {
;                     const size_t off = (size_t)row * 1024 + colb + bj * 128;
;                     const u32x4 w = xw[k][bj];
;                     const f32x4 x0 = (f32x4){bf_lo(w.x), bf_hi(w.x), bf_lo(w.y), bf_hi(w.y)}, x1 = (f32x4){bf_lo(w.z), bf_hi(w.z), bf_lo(w.w), bf_hi(w.w)};
;                     f32x4 d0 = acc[ai][bj][m][0], d1 = acc[ai][bj][m][1];
;                     if (MODE == 2) { const float r2 = rs8[ai][m] * rs8[ai][m]; d0 = d0 * r2; d1 = d1 * r2; }
;                     if (MODE == 1) {
;                         const float rs = rs8[ai][m];
;                         const u32x4 q = pw[k][bj];
;                         const f32x4 p0 = (f32x4){bf_lo(q.x), bf_hi(q.x), bf_lo(q.y), bf_hi(q.y)}, p1 = (f32x4){bf_lo(q.z), bf_hi(q.z), bf_lo(q.w), bf_hi(q.w)};
; #pragma unroll
;                         for (int i = 0; i < 4; ++i) { d0[i] = p0[i] * __builtin_amdgcn_rcpf(1.0f + __expf(-d0[i] * rs)); d1[i] = p1[i] * __builtin_amdgcn_rcpf(1.0f + __expf(-d1[i] * rs)); }
;                     }
.LBB0_1811:
	v_lshl_add_u32 v132, s38, 8, v198
	v_or_b32_e32 v188, 32, v132
	v_ashrrev_i32_e32 v133, 31, v132
	v_ashrrev_i32_e32 v189, 31, v188
	v_lshlrev_b64 v[130:131], 6, v[132:133]
	v_lshlrev_b64 v[142:143], 6, v[188:189]
	v_lshl_add_u64 v[130:131], v[170:171], 0, v[130:131]
	v_lshl_add_u64 v[142:143], v[170:171], 0, v[142:143]
	global_load_dwordx4 v[134:137], v[130:131], off
	v_or_b32_e32 v186, 48, v132
	global_load_dwordx4 v[142:145], v[142:143], off
	v_or_b32_e32 v130, 16, v132
	v_ashrrev_i32_e32 v131, 31, v130
	v_lshlrev_b64 v[138:139], 6, v[130:131]
	v_lshl_add_u64 v[138:139], v[170:171], 0, v[138:139]
	global_load_dwordx4 v[138:141], v[138:139], off
	v_ashrrev_i32_e32 v187, 31, v186
	v_lshlrev_b64 v[146:147], 6, v[186:187]
	v_lshl_add_u64 v[146:147], v[170:171], 0, v[146:147]
	global_load_dwordx4 v[146:149], v[146:147], off
	v_add_u32_e32 v184, 0x80, v132
	v_add_u32_e32 v182, 0x90, v132
	v_ashrrev_i32_e32 v185, 31, v184
	v_ashrrev_i32_e32 v183, 31, v182
	v_lshlrev_b64 v[150:151], 6, v[184:185]
	v_lshlrev_b64 v[154:155], 6, v[182:183]
	v_lshl_add_u64 v[150:151], v[170:171], 0, v[150:151]
	v_lshl_add_u64 v[154:155], v[170:171], 0, v[154:155]
	global_load_dwordx4 v[150:153], v[150:151], off
	v_add_u32_e32 v177, 64, v216
	global_load_dwordx4 v[154:157], v[154:155], off
	v_cmp_lt_i32_e32 vcc, v217, v177
	v_add_u32_e32 v180, 0xa0, v132
	v_add_u32_e32 v178, 0xb0, v132
	v_cndmask_b32_e32 v194, v219, v217, vcc
	v_lshlrev_b32_e32 v196, 2, v194
	v_cmp_lt_i32_e32 vcc, v229, v177
	v_ashrrev_i32_e32 v181, 31, v180
	v_ashrrev_i32_e32 v179, 31, v178
	v_cndmask_b32_e32 v177, v219, v229, vcc
	v_lshlrev_b32_e32 v177, 2, v177
	v_lshlrev_b64 v[158:159], 6, v[180:181]
	v_lshlrev_b64 v[190:191], 6, v[178:179]
	v_lshl_add_u64 v[158:159], v[170:171], 0, v[158:159]
	v_lshl_add_u64 v[190:191], v[170:171], 0, v[190:191]
	global_load_dwordx4 v[158:161], v[158:159], off
	v_lshl_or_b32 v176, s39, 8, v200
	global_load_dwordx4 v[190:193], v[190:191], off
	v_lshlrev_b64 v[132:133], 10, v[132:133]
	v_lshlrev_b64 v[130:131], 10, v[130:131]
	s_mov_b64 s[38:39], -1
	s_waitcnt vmcnt(0)
	v_mov_b32_e32 v194, v135
	v_mov_b32_e32 v195, v136
	v_mov_b32_e32 v135, v137
	v_pk_add_f32 v[134:135], v[194:195], v[134:135]
	v_mov_b32_e32 v136, v139
	v_mov_b32_e32 v137, v140
	v_mov_b32_e32 v139, v141
	v_pk_add_f32 v[136:137], v[136:137], v[138:139]
	v_mov_b32_e32 v139, v134
	v_mov_b32_e32 v138, v136
	v_mov_b32_e32 v134, v137
	v_pk_add_f32 v[134:135], v[138:139], v[134:135]
	ds_bpermute_b32 v137, v196, v135
	ds_bpermute_b32 v136, v196, v134
	v_mov_b32_e32 v139, v148
	s_waitcnt lgkmcnt(0)
	v_pk_add_f32 v[134:135], v[134:135], v[136:137]
	ds_bpermute_b32 v137, v177, v135
	ds_bpermute_b32 v136, v177, v134
	s_waitcnt lgkmcnt(0)
	v_pk_add_f32 v[134:135], v[134:135], v[136:137]
	v_mov_b64_e32 v[136:137], s[30:31]
	v_pk_fma_f32 v[134:135], v[134:135], s[28:29], v[136:137] op_sel_hi:[1,0,0]
	s_nop 0
	v_mul_f32_e32 v138, 0x4b800000, v135
	v_cmp_gt_f32_e64 s[42:43], s31, v135
	v_cmp_gt_f32_e32 vcc, s31, v134
	s_nop 0
	v_cndmask_b32_e64 v135, v135, v138, s[42:43]
	v_rsq_f32_e32 v135, v135
	s_nop 0
	v_mul_f32_e32 v138, 0x45800000, v135
	v_cndmask_b32_e64 v209, v135, v138, s[42:43]
	v_mul_f32_e32 v135, 0x4b800000, v134
	v_cndmask_b32_e32 v134, v134, v135, vcc
	v_rsq_f32_e32 v134, v134
	v_mov_b32_e32 v138, v147
	v_mov_b32_e32 v147, v149
	v_pk_add_f32 v[138:139], v[138:139], v[146:147]
	v_mul_f32_e32 v135, 0x45800000, v134
	v_cndmask_b32_e32 v208, v134, v135, vcc
	v_mov_b32_e32 v134, v143
	v_mov_b32_e32 v135, v144
	v_mov_b32_e32 v143, v145
	v_pk_add_f32 v[134:135], v[134:135], v[142:143]
	v_mov_b32_e32 v140, v138
	v_mov_b32_e32 v141, v134
	v_mov_b32_e32 v134, v139
	v_pk_add_f32 v[134:135], v[140:141], v[134:135]
	ds_bpermute_b32 v139, v196, v135
	ds_bpermute_b32 v138, v196, v134
	v_mul_f32_e64 v122, v209, -v122
	v_mul_f32_e32 v122, 0x3fb8aa3b, v122
	v_exp_f32_e32 v122, v122
	v_mul_f32_e64 v126, v209, -v126
	s_waitcnt lgkmcnt(0)
	v_pk_add_f32 v[134:135], v[134:135], v[138:139]
	ds_bpermute_b32 v139, v177, v135
	ds_bpermute_b32 v138, v177, v134
	v_add_f32_e32 v122, 1.0, v122
	v_rcp_f32_e32 v210, v122
	v_mul_f32_e64 v122, v209, -v127
	v_mul_f32_e32 v122, 0x3fb8aa3b, v122
	s_waitcnt lgkmcnt(0)
	v_pk_add_f32 v[134:135], v[134:135], v[138:139]
	v_mov_b32_e32 v139, v156
	v_pk_fma_f32 v[134:135], v[134:135], s[28:29], v[136:137] op_sel_hi:[1,0,0]
	v_exp_f32_e32 v122, v122
	v_mul_f32_e32 v138, 0x4b800000, v135
	v_cmp_gt_f32_e64 s[42:43], s31, v135
	v_cmp_gt_f32_e32 vcc, s31, v134
	v_add_f32_e32 v122, 1.0, v122
	v_cndmask_b32_e64 v135, v135, v138, s[42:43]
	v_rsq_f32_e32 v135, v135
	v_rcp_f32_e32 v127, v122
	v_mul_f32_e64 v122, v209, -v123
	v_mul_f32_e64 v123, v209, -v124
	v_mul_f32_e32 v138, 0x45800000, v135
	v_cndmask_b32_e64 v207, v135, v138, s[42:43]
	v_mul_f32_e32 v135, 0x4b800000, v134
	v_cndmask_b32_e32 v134, v134, v135, vcc
	v_rsq_f32_e32 v134, v134
	v_mov_b32_e32 v138, v155
	v_mov_b32_e32 v155, v157
	v_pk_add_f32 v[138:139], v[138:139], v[154:155]
	v_mul_f32_e32 v135, 0x45800000, v134
	v_cndmask_b32_e32 v206, v134, v135, vcc
	v_mov_b32_e32 v134, v151
	v_mov_b32_e32 v135, v152
	v_mov_b32_e32 v151, v153
	v_pk_add_f32 v[134:135], v[134:135], v[150:151]
	v_mov_b32_e32 v140, v138
	v_mov_b32_e32 v141, v134
	v_mov_b32_e32 v134, v139
	v_pk_add_f32 v[134:135], v[140:141], v[134:135]
	ds_bpermute_b32 v139, v196, v135
	ds_bpermute_b32 v138, v196, v134
	v_mul_f32_e32 v122, 0x3fb8aa3b, v122
	v_mul_f32_e32 v123, 0x3fb8aa3b, v123
	v_exp_f32_e32 v122, v122
	v_exp_f32_e32 v123, v123
	s_waitcnt lgkmcnt(0)
; __device__ __forceinline__ float bf_lo(unsigned w) { return __uint_as_float(w << 16); }
; __device__ __forceinline__ float bf_hi(unsigned w) { return __uint_as_float(w & 0xffff0000u); }
;     __device__ __forceinline__ void operator()(const f32x4 (&acc)[2][2][4][2], const Unit& u, int wr, int wc, int fr, int fq) const {
;     ...
;             for (int k = 0; k < NB; ++k)
; #pragma unroll
;                 for (int bj = 0; bj < 2; ++bj) {
;                     const int ai = (g * NB + k) >> 2, m = (g * NB + k) & 3;
;                     const size_t off = (size_t)(u.pm * 256 + ai * 128 + wr * 64 + m * 16 + fr) * 1024 + colb + bj * 128;
;                     xw[k][bj] = *(const u32x4*)(xold + off);
;                     if (MODE == 1) pw[k][bj] = *(const u32x4*)(pg + off);
;                 }
; #pragma unroll
;             for (int k = 0; k < NB; ++k) {
;                 const int ai = (g * NB + k) >> 2, m = (g * NB + k) & 3;
;                 const int row = u.pm * 256 + ai * 128 + wr * 64 + m * 16 + fr;
;                 float ss = 0.f;
; #pragma unroll
;                 for (int bj = 0; bj < 2; ++bj) {
;                     const size_t off = (size_t)row * 1024 + colb + bj * 128;
;                     const u32x4 w = xw[k][bj];
;                     const f32x4 x0 = (f32x4){bf_lo(w.x), bf_hi(w.x), bf_lo(w.y), bf_hi(w.y)}, x1 = (f32x4){bf_lo(w.z), bf_hi(w.z), bf_lo(w.w), bf_hi(w.w)};
;                     f32x4 d0 = acc[ai][bj][m][0], d1 = acc[ai][bj][m][1];
;                     if (MODE == 2) { const float r2 = rs8[ai][m] * rs8[ai][m]; d0 = d0 * r2; d1 = d1 * r2; }
;                     if (MODE == 1) {
;                         const float rs = rs8[ai][m];
;                         const u32x4 q = pw[k][bj];
;                         const f32x4 p0 = (f32x4){bf_lo(q.x), bf_hi(q.x), bf_lo(q.y), bf_hi(q.y)}, p1 = (f32x4){bf_lo(q.z), bf_hi(q.z), bf_lo(q.w), bf_hi(q.w)};
; #pragma unroll
;                         for (int i = 0; i < 4; ++i) { d0[i] = p0[i] * __builtin_amdgcn_rcpf(1.0f + __expf(-d0[i] * rs)); d1[i] = p1[i] * __builtin_amdgcn_rcpf(1.0f + __expf(-d1[i] * rs)); }
;                     }
	v_pk_add_f32 v[134:135], v[134:135], v[138:139]
	ds_bpermute_b32 v139, v177, v135
	ds_bpermute_b32 v138, v177, v134
	v_add_f32_e32 v122, 1.0, v122
	v_add_f32_e32 v123, 1.0, v123
	v_rcp_f32_e32 v211, v122
	v_mul_f32_e64 v122, v209, -v128
	s_waitcnt lgkmcnt(0)
	v_pk_add_f32 v[134:135], v[134:135], v[138:139]
	v_mov_b32_e32 v139, v192
	v_pk_fma_f32 v[134:135], v[134:135], s[28:29], v[136:137] op_sel_hi:[1,0,0]
	v_rcp_f32_e32 v128, v123
	v_mul_f32_e32 v138, 0x4b800000, v135
	v_cmp_gt_f32_e64 s[42:43], s31, v135
	v_cmp_gt_f32_e32 vcc, s31, v134
	v_mul_f32_e64 v123, v209, -v129
	v_cndmask_b32_e64 v135, v135, v138, s[42:43]
	v_rsq_f32_e32 v135, v135
	v_mul_f32_e32 v126, 0x3fb8aa3b, v126
	v_mul_f32_e32 v122, 0x3fb8aa3b, v122
	v_mul_f32_e32 v123, 0x3fb8aa3b, v123
	v_mul_f32_e32 v138, 0x45800000, v135
	v_cndmask_b32_e64 v205, v135, v138, s[42:43]
	v_mul_f32_e32 v135, 0x4b800000, v134
	v_cndmask_b32_e32 v134, v134, v135, vcc
	v_rsq_f32_e32 v134, v134
	v_mov_b32_e32 v138, v191
	v_mov_b32_e32 v191, v193
	v_pk_add_f32 v[138:139], v[138:139], v[190:191]
	v_mul_f32_e32 v135, 0x45800000, v134
	v_cndmask_b32_e32 v204, v134, v135, vcc
	v_mov_b32_e32 v134, v159
	v_mov_b32_e32 v135, v160
	v_mov_b32_e32 v159, v161
	v_pk_add_f32 v[134:135], v[134:135], v[158:159]
	v_mov_b32_e32 v140, v138
	v_mov_b32_e32 v141, v134
	v_mov_b32_e32 v134, v139
	v_pk_add_f32 v[134:135], v[140:141], v[134:135]
	ds_bpermute_b32 v139, v196, v135
	ds_bpermute_b32 v138, v196, v134
	v_mul_f32_e64 v124, v209, -v125
	v_exp_f32_e32 v126, v126
	v_exp_f32_e32 v122, v122
	v_exp_f32_e32 v123, v123
	s_waitcnt lgkmcnt(0)
	v_pk_add_f32 v[134:135], v[134:135], v[138:139]
	ds_bpermute_b32 v139, v177, v135
	ds_bpermute_b32 v138, v177, v134
	v_ashrrev_i32_e32 v177, 31, v176
	v_lshl_add_u64 v[192:193], v[132:133], 0, v[176:177]
	v_lshlrev_b64 v[132:133], 1, v[192:193]
	v_lshl_add_u64 v[190:191], v[130:131], 0, v[176:177]
	s_waitcnt lgkmcnt(0)
	v_pk_add_f32 v[134:135], v[134:135], v[138:139]
	v_lshlrev_b64 v[130:131], 1, v[190:191]
	v_pk_fma_f32 v[134:135], v[134:135], s[28:29], v[136:137] op_sel_hi:[1,0,0]
	v_mul_f32_e32 v124, 0x3fb8aa3b, v124
	v_mul_f32_e32 v136, 0x4b800000, v135
	v_cmp_gt_f32_e64 s[42:43], s31, v135
	v_cmp_gt_f32_e32 vcc, s31, v134
	v_exp_f32_e32 v124, v124
	v_cndmask_b32_e64 v135, v135, v136, s[42:43]
	v_rsq_f32_e32 v135, v135
	v_mul_f32_e64 v114, v209, -v114
	v_add_f32_e32 v126, 1.0, v126
	v_add_f32_e32 v122, 1.0, v122
	v_mul_f32_e32 v136, 0x45800000, v135
	v_cndmask_b32_e64 v203, v135, v136, s[42:43]
	v_mul_f32_e32 v135, 0x4b800000, v134
	v_cndmask_b32_e32 v134, v134, v135, vcc
	v_rsq_f32_e32 v134, v134
	v_add_f32_e32 v123, 1.0, v123
	v_mul_f32_e32 v114, 0x3fb8aa3b, v114
	v_rcp_f32_e32 v126, v126
	v_mul_f32_e32 v135, 0x45800000, v134
	v_cndmask_b32_e32 v202, v134, v135, vcc
	v_lshl_add_u64 v[134:135], s[46:47], 0, v[132:133]
	global_load_dwordx4 v[158:161], v[134:135], off
	v_lshl_add_u64 v[134:135], s[18:19], 0, v[132:133]
	global_load_dwordx4 v[154:157], v[134:135], off
	v_or_b32_e32 v132, 0x100, v132
	v_lshl_add_u64 v[134:135], s[46:47], 0, v[132:133]
	global_load_dwordx4 v[150:153], v[134:135], off
	v_lshl_add_u64 v[132:133], s[18:19], 0, v[132:133]
	global_load_dwordx4 v[142:145], v[132:133], off
	v_lshl_add_u64 v[132:133], s[46:47], 0, v[130:131]
	global_load_dwordx4 v[146:149], v[132:133], off
	v_lshl_add_u64 v[132:133], s[18:19], 0, v[130:131]
	global_load_dwordx4 v[138:141], v[132:133], off
	v_or_b32_e32 v130, 0x100, v130
	v_lshl_add_u64 v[132:133], s[46:47], 0, v[130:131]
	v_lshl_add_u64 v[130:131], s[18:19], 0, v[130:131]
	global_load_dwordx4 v[134:137], v[132:133], off
	v_rcp_f32_e32 v122, v122
	global_load_dwordx4 v[130:133], v[130:131], off
	v_rcp_f32_e32 v123, v123
	v_add_f32_e32 v124, 1.0, v124
	v_exp_f32_e32 v114, v114
	v_rcp_f32_e32 v129, v124
	v_mul_f32_e64 v118, v209, -v118
	v_mul_f32_e32 v118, 0x3fb8aa3b, v118
	v_add_f32_e32 v114, 1.0, v114
	v_exp_f32_e32 v118, v118
	v_mul_f32_e64 v106, v208, -v106
	v_mul_f32_e32 v106, 0x3fb8aa3b, v106
	v_exp_f32_e32 v106, v106
	v_add_f32_e32 v118, 1.0, v118
	v_rcp_f32_e32 v118, v118
	v_mul_f32_e64 v98, v208, -v98
	v_add_f32_e32 v106, 1.0, v106
	v_mul_f32_e32 v98, 0x3fb8aa3b, v98
	v_exp_f32_e32 v98, v98
	v_mul_f32_e64 v110, v208, -v110
	v_mul_f32_e32 v110, 0x3fb8aa3b, v110
	v_exp_f32_e32 v110, v110
	v_add_f32_e32 v98, 1.0, v98
	v_mul_f32_e64 v102, v208, -v102
	v_mul_f32_e32 v102, 0x3fb8aa3b, v102
	v_exp_f32_e32 v102, v102
	v_add_f32_e32 v110, 1.0, v110
	v_rcp_f32_e32 v110, v110
	v_mul_f32_e64 v90, v207, -v90
	v_add_f32_e32 v102, 1.0, v102
	v_rcp_f32_e32 v102, v102
	v_mul_f32_e32 v90, 0x3fb8aa3b, v90
	v_exp_f32_e32 v90, v90
	v_mul_f32_e64 v82, v207, -v82
	v_mul_f32_e32 v82, 0x3fb8aa3b, v82
	v_exp_f32_e32 v82, v82
	v_add_f32_e32 v90, 1.0, v90
	v_mul_f32_e64 v94, v207, -v94
	v_mul_f32_e32 v94, 0x3fb8aa3b, v94
	v_add_f32_e32 v82, 1.0, v82
	v_exp_f32_e32 v94, v94
	v_mul_f32_e64 v86, v207, -v86
	v_mul_f32_e32 v86, 0x3fb8aa3b, v86
	v_exp_f32_e32 v86, v86
	v_add_f32_e32 v94, 1.0, v94
	v_mul_f32_e64 v74, v206, -v74
	v_rcp_f32_e32 v94, v94
	v_mul_f32_e32 v74, 0x3fb8aa3b, v74
	v_add_f32_e32 v86, 1.0, v86
	v_exp_f32_e32 v74, v74
	v_rcp_f32_e32 v86, v86
	v_mul_f32_e64 v66, v206, -v66
	v_mul_f32_e32 v66, 0x3fb8aa3b, v66
	v_add_f32_e32 v74, 1.0, v74
	v_exp_f32_e32 v66, v66
	v_mul_f32_e64 v78, v206, -v78
	v_mul_f32_e32 v78, 0x3fb8aa3b, v78
	v_exp_f32_e32 v78, v78
	v_add_f32_e32 v66, 1.0, v66
	v_mul_f32_e64 v70, v206, -v70
	v_mul_f32_e32 v70, 0x3fb8aa3b, v70
	v_exp_f32_e32 v70, v70
	v_add_f32_e32 v78, 1.0, v78
	v_rcp_f32_e32 v78, v78
	s_waitcnt vmcnt(7)
	v_lshlrev_b32_e32 v194, 16, v158
	v_and_b32_e32 v195, 0xffff0000, v158
	v_lshlrev_b32_e32 v158, 16, v159
	v_and_b32_e32 v159, 0xffff0000, v159
	s_waitcnt vmcnt(6)
; __device__ __forceinline__ float bf_lo(unsigned w) { return __uint_as_float(w << 16); }
; __device__ __forceinline__ float bf_hi(unsigned w) { return __uint_as_float(w & 0xffff0000u); }
; __device__ __forceinline__ float dot4(f32x4 a) { return (a[0] * a[0] + a[1] * a[1]) + (a[2] * a[2] + a[3] * a[3]); }
; __device__ __forceinline__ u32x4 pack8(f32x4 a, f32x4 b) { u32x4 w; w.x = cvt_pk_bf16(a[0], a[1]); w.y = cvt_pk_bf16(a[2], a[3]); w.z = cvt_pk_bf16(b[0], b[1]); w.w = cvt_pk_bf16(b[2], b[3]); return w; }
;     __device__ __forceinline__ void operator()(const f32x4 (&acc)[2][2][4][2], const Unit& u, int wr, int wc, int fr, int fq) const {
;     ...
;             for (int k = 0; k < NB; ++k) {
;                 const int ai = (g * NB + k) >> 2, m = (g * NB + k) & 3;
;                 const int row = u.pm * 256 + ai * 128 + wr * 64 + m * 16 + fr;
;                 float ss = 0.f;
; #pragma unroll
;                 for (int bj = 0; bj < 2; ++bj) {
;                     const size_t off = (size_t)row * 1024 + colb + bj * 128;
;                     const u32x4 w = xw[k][bj];
;                     const f32x4 x0 = (f32x4){bf_lo(w.x), bf_hi(w.x), bf_lo(w.y), bf_hi(w.y)}, x1 = (f32x4){bf_lo(w.z), bf_hi(w.z), bf_lo(w.w), bf_hi(w.w)};
;                     f32x4 d0 = acc[ai][bj][m][0], d1 = acc[ai][bj][m][1];
;                     if (MODE == 2) { const float r2 = rs8[ai][m] * rs8[ai][m]; d0 = d0 * r2; d1 = d1 * r2; }
;                     if (MODE == 1) {
;                         const float rs = rs8[ai][m];
;                         const u32x4 q = pw[k][bj];
;                         const f32x4 p0 = (f32x4){bf_lo(q.x), bf_hi(q.x), bf_lo(q.y), bf_hi(q.y)}, p1 = (f32x4){bf_lo(q.z), bf_hi(q.z), bf_lo(q.w), bf_hi(q.w)};
; #pragma unroll
;                         for (int i = 0; i < 4; ++i) { d0[i] = p0[i] * __builtin_amdgcn_rcpf(1.0f + __expf(-d0[i] * rs)); d1[i] = p1[i] * __builtin_amdgcn_rcpf(1.0f + __expf(-d1[i] * rs)); }
;                     }
;                     const f32x4 y0 = x0 + d0, y1 = x1 + d1;
;                     if (LAST) { *(f32x4*)(xout + off) = y0; *(f32x4*)(xout + off + 4) = y1; }
;                     else { ss += dot4(y0) + dot4(y1); *(u32x4*)(xb + off) = pack8(y0, y1); }
	v_lshlrev_b32_e32 v212, 16, v154
	v_and_b32_e32 v213, 0xffff0000, v154
	v_lshlrev_b32_e32 v154, 16, v155
	v_and_b32_e32 v155, 0xffff0000, v155
	v_lshlrev_b32_e32 v196, 16, v160
	v_and_b32_e32 v197, 0xffff0000, v160
	v_lshlrev_b32_e32 v160, 16, v161
	v_and_b32_e32 v161, 0xffff0000, v161
	v_lshlrev_b32_e32 v214, 16, v156
	v_and_b32_e32 v215, 0xffff0000, v156
	v_lshlrev_b32_e32 v156, 16, v157
	v_and_b32_e32 v157, 0xffff0000, v157
	v_pk_fma_f32 v[124:125], v[122:123], v[154:155], v[158:159]
	v_pk_fma_f32 v[122:123], v[126:127], v[212:213], v[194:195]
	v_lshl_add_u64 v[154:155], v[192:193], 2, s[52:53]
	v_pk_fma_f32 v[128:129], v[128:129], v[156:157], v[160:161]
	v_pk_fma_f32 v[126:127], v[210:211], v[214:215], v[196:197]
	global_store_dwordx4 v[154:155], v[122:125], off nt
	global_store_dwordx4 v[154:155], v[126:129], off offset:16 nt
	s_waitcnt vmcnt(6)
	v_lshlrev_b32_e32 v156, 16, v144
	v_lshlrev_b32_e32 v122, 16, v150
	v_and_b32_e32 v123, 0xffff0000, v150
	v_rcp_f32_e32 v150, v114
	v_mul_f32_e64 v114, v209, -v119
	v_mul_f32_e32 v114, 0x3fb8aa3b, v114
	v_exp_f32_e32 v114, v114
	v_lshlrev_b32_e32 v124, 16, v151
	v_and_b32_e32 v125, 0xffff0000, v151
	v_lshlrev_b32_e32 v126, 16, v152
	v_add_f32_e32 v114, 1.0, v114
	v_rcp_f32_e32 v119, v114
	v_mul_f32_e64 v114, v209, -v115
	v_mul_f32_e64 v115, v209, -v116
	v_mul_f32_e32 v114, 0x3fb8aa3b, v114
	v_mul_f32_e32 v115, 0x3fb8aa3b, v115
	v_exp_f32_e32 v114, v114
	v_exp_f32_e32 v115, v115
	v_mul_f32_e64 v116, v209, -v117
	v_mul_f32_e32 v116, 0x3fb8aa3b, v116
	v_add_f32_e32 v114, 1.0, v114
	v_add_f32_e32 v115, 1.0, v115
	v_rcp_f32_e32 v151, v114
	v_mul_f32_e64 v114, v209, -v120
	v_rcp_f32_e32 v120, v115
	v_mul_f32_e64 v115, v209, -v121
	v_mul_f32_e32 v114, 0x3fb8aa3b, v114
	v_mul_f32_e32 v115, 0x3fb8aa3b, v115
	v_exp_f32_e32 v114, v114
	v_exp_f32_e32 v115, v115
	v_exp_f32_e32 v116, v116
	v_and_b32_e32 v127, 0xffff0000, v152
	v_add_f32_e32 v114, 1.0, v114
	v_add_f32_e32 v115, 1.0, v115
	v_rcp_f32_e32 v114, v114
	v_rcp_f32_e32 v115, v115
	v_lshlrev_b32_e32 v128, 16, v153
	v_and_b32_e32 v129, 0xffff0000, v153
	v_lshlrev_b32_e32 v152, 16, v142
	v_and_b32_e32 v153, 0xffff0000, v142
	v_lshlrev_b32_e32 v142, 16, v143
	v_and_b32_e32 v143, 0xffff0000, v143
	v_add_f32_e32 v116, 1.0, v116
	v_rcp_f32_e32 v121, v116
	v_pk_fma_f32 v[116:117], v[114:115], v[142:143], v[124:125]
	v_pk_fma_f32 v[114:115], v[118:119], v[152:153], v[122:123]
	v_rcp_f32_e32 v122, v106
	v_mul_f32_e64 v106, v208, -v111
	v_mul_f32_e32 v106, 0x3fb8aa3b, v106
	v_exp_f32_e32 v106, v106
	v_and_b32_e32 v157, 0xffff0000, v144
	v_lshlrev_b32_e32 v144, 16, v145
	v_and_b32_e32 v145, 0xffff0000, v145
	v_add_f32_e32 v106, 1.0, v106
	v_rcp_f32_e32 v111, v106
	v_mul_f32_e64 v106, v208, -v107
	v_mul_f32_e64 v107, v208, -v108
	v_mul_f32_e32 v106, 0x3fb8aa3b, v106
	v_mul_f32_e32 v107, 0x3fb8aa3b, v107
	v_exp_f32_e32 v106, v106
	v_exp_f32_e32 v107, v107
	v_mul_f32_e64 v108, v208, -v109
	v_mul_f32_e32 v108, 0x3fb8aa3b, v108
	v_add_f32_e32 v106, 1.0, v106
	v_add_f32_e32 v107, 1.0, v107
	v_rcp_f32_e32 v123, v106
	v_mul_f32_e64 v106, v208, -v112
	v_rcp_f32_e32 v112, v107
	v_mul_f32_e64 v107, v208, -v113
	v_mul_f32_e32 v106, 0x3fb8aa3b, v106
	v_mul_f32_e32 v107, 0x3fb8aa3b, v107
	v_exp_f32_e32 v106, v106
	v_exp_f32_e32 v107, v107
	v_exp_f32_e32 v108, v108
	v_pk_fma_f32 v[120:121], v[120:121], v[144:145], v[128:129]
	v_add_f32_e32 v106, 1.0, v106
	v_add_f32_e32 v107, 1.0, v107
	v_rcp_f32_e32 v106, v106
	v_rcp_f32_e32 v107, v107
	v_pk_fma_f32 v[118:119], v[150:151], v[156:157], v[126:127]
	global_store_dwordx4 v[154:155], v[114:117], off offset:512 nt
	global_store_dwordx4 v[154:155], v[118:121], off offset:528 nt
	s_waitcnt vmcnt(6)
	v_lshlrev_b32_e32 v128, 16, v139
	v_lshlrev_b32_e32 v116, 16, v147
	v_and_b32_e32 v117, 0xffff0000, v147
	v_and_b32_e32 v129, 0xffff0000, v139
	v_add_f32_e32 v108, 1.0, v108
	v_rcp_f32_e32 v113, v108
	v_pk_fma_f32 v[108:109], v[106:107], v[128:129], v[116:117]
	v_rcp_f32_e32 v116, v98
	v_mul_f32_e64 v98, v208, -v103
	v_mul_f32_e32 v98, 0x3fb8aa3b, v98
	v_exp_f32_e32 v98, v98
	v_lshlrev_b32_e32 v114, 16, v146
	v_and_b32_e32 v115, 0xffff0000, v146
	v_lshlrev_b32_e32 v124, 16, v138
	v_add_f32_e32 v98, 1.0, v98
	v_rcp_f32_e32 v103, v98
	v_mul_f32_e64 v98, v208, -v99
	v_mul_f32_e64 v99, v208, -v100
	v_mul_f32_e32 v98, 0x3fb8aa3b, v98
	v_mul_f32_e32 v99, 0x3fb8aa3b, v99
	v_exp_f32_e32 v98, v98
	v_exp_f32_e32 v99, v99
	v_mul_f32_e64 v100, v208, -v101
	v_mul_f32_e32 v100, 0x3fb8aa3b, v100
	v_add_f32_e32 v98, 1.0, v98
	v_add_f32_e32 v99, 1.0, v99
	v_rcp_f32_e32 v117, v98
	v_mul_f32_e64 v98, v208, -v104
	v_rcp_f32_e32 v104, v99
	v_mul_f32_e64 v99, v208, -v105
	v_mul_f32_e32 v98, 0x3fb8aa3b, v98
	v_mul_f32_e32 v99, 0x3fb8aa3b, v99
	v_exp_f32_e32 v98, v98
	v_exp_f32_e32 v99, v99
	v_exp_f32_e32 v100, v100
	v_and_b32_e32 v125, 0xffff0000, v138
	v_add_f32_e32 v98, 1.0, v98
	v_add_f32_e32 v99, 1.0, v99
	v_rcp_f32_e32 v98, v98
	v_rcp_f32_e32 v99, v99
	v_add_f32_e32 v100, 1.0, v100
	v_rcp_f32_e32 v105, v100
	v_lshlrev_b32_e32 v118, 16, v148
	v_and_b32_e32 v119, 0xffff0000, v148
	v_lshlrev_b32_e32 v120, 16, v149
	v_and_b32_e32 v121, 0xffff0000, v149
	v_lshlrev_b32_e32 v126, 16, v140
	v_and_b32_e32 v127, 0xffff0000, v140
	v_lshlrev_b32_e32 v138, 16, v141
	v_and_b32_e32 v139, 0xffff0000, v141
	v_pk_fma_f32 v[106:107], v[110:111], v[124:125], v[114:115]
	v_lshl_add_u64 v[114:115], v[190:191], 2, s[52:53]
	v_pk_fma_f32 v[112:113], v[112:113], v[138:139], v[120:121]
	v_pk_fma_f32 v[110:111], v[122:123], v[126:127], v[118:119]
	global_store_dwordx4 v[114:115], v[106:109], off nt
	global_store_dwordx4 v[114:115], v[110:113], off offset:16 nt
	s_waitcnt vmcnt(6)
; __device__ __forceinline__ float bf_lo(unsigned w) { return __uint_as_float(w << 16); }
; __device__ __forceinline__ float bf_hi(unsigned w) { return __uint_as_float(w & 0xffff0000u); }
; __device__ __forceinline__ float dot4(f32x4 a) { return (a[0] * a[0] + a[1] * a[1]) + (a[2] * a[2] + a[3] * a[3]); }
; __device__ __forceinline__ u32x4 pack8(f32x4 a, f32x4 b) { u32x4 w; w.x = cvt_pk_bf16(a[0], a[1]); w.y = cvt_pk_bf16(a[2], a[3]); w.z = cvt_pk_bf16(b[0], b[1]); w.w = cvt_pk_bf16(b[2], b[3]); return w; }
;     __device__ __forceinline__ void operator()(const f32x4 (&acc)[2][2][4][2], const Unit& u, int wr, int wc, int fr, int fq) const {
;     ...
;             for (int k = 0; k < NB; ++k) {
;                 const int ai = (g * NB + k) >> 2, m = (g * NB + k) & 3;
;                 const int row = u.pm * 256 + ai * 128 + wr * 64 + m * 16 + fr;
;                 float ss = 0.f;
; #pragma unroll
;                 for (int bj = 0; bj < 2; ++bj) {
;                     const size_t off = (size_t)row * 1024 + colb + bj * 128;
;                     const u32x4 w = xw[k][bj];
;                     const f32x4 x0 = (f32x4){bf_lo(w.x), bf_hi(w.x), bf_lo(w.y), bf_hi(w.y)}, x1 = (f32x4){bf_lo(w.z), bf_hi(w.z), bf_lo(w.w), bf_hi(w.w)};
;                     f32x4 d0 = acc[ai][bj][m][0], d1 = acc[ai][bj][m][1];
;                     if (MODE == 2) { const float r2 = rs8[ai][m] * rs8[ai][m]; d0 = d0 * r2; d1 = d1 * r2; }
;                     if (MODE == 1) {
;                         const float rs = rs8[ai][m];
;                         const u32x4 q = pw[k][bj];
;                         const f32x4 p0 = (f32x4){bf_lo(q.x), bf_hi(q.x), bf_lo(q.y), bf_hi(q.y)}, p1 = (f32x4){bf_lo(q.z), bf_hi(q.z), bf_lo(q.w), bf_hi(q.w)};
; #pragma unroll
;                         for (int i = 0; i < 4; ++i) { d0[i] = p0[i] * __builtin_amdgcn_rcpf(1.0f + __expf(-d0[i] * rs)); d1[i] = p1[i] * __builtin_amdgcn_rcpf(1.0f + __expf(-d1[i] * rs)); }
;                     }
;                     const f32x4 y0 = x0 + d0, y1 = x1 + d1;
;                     if (LAST) { *(f32x4*)(xout + off) = y0; *(f32x4*)(xout + off + 4) = y1; }
;                     else { ss += dot4(y0) + dot4(y1); *(u32x4*)(xb + off) = pack8(y0, y1); }
	v_lshlrev_b32_e32 v118, 16, v130
	v_lshlrev_b32_e32 v106, 16, v134
	v_and_b32_e32 v107, 0xffff0000, v134
	v_lshlrev_b32_e32 v108, 16, v135
	v_and_b32_e32 v109, 0xffff0000, v135
	v_and_b32_e32 v119, 0xffff0000, v130
	v_lshlrev_b32_e32 v122, 16, v131
	v_and_b32_e32 v123, 0xffff0000, v131
	v_lshlrev_b32_e32 v110, 16, v136
	v_and_b32_e32 v111, 0xffff0000, v136
	v_lshlrev_b32_e32 v112, 16, v137
	v_and_b32_e32 v113, 0xffff0000, v137
	v_lshlrev_b32_e32 v120, 16, v132
	v_and_b32_e32 v121, 0xffff0000, v132
	v_lshlrev_b32_e32 v124, 16, v133
	v_and_b32_e32 v125, 0xffff0000, v133
	v_pk_fma_f32 v[100:101], v[98:99], v[122:123], v[108:109]
	v_pk_fma_f32 v[98:99], v[102:103], v[118:119], v[106:107]
	v_pk_fma_f32 v[104:105], v[104:105], v[124:125], v[112:113]
	v_pk_fma_f32 v[102:103], v[116:117], v[120:121], v[110:111]
	global_store_dwordx4 v[114:115], v[98:101], off offset:512 nt
	global_store_dwordx4 v[114:115], v[102:105], off offset:528 nt
	v_rcp_f32_e32 v138, v90
	v_lshlrev_b64 v[98:99], 10, v[188:189]
	v_lshl_add_u64 v[128:129], v[98:99], 0, v[176:177]
	v_lshlrev_b64 v[98:99], 1, v[128:129]
	v_lshl_add_u64 v[100:101], s[46:47], 0, v[98:99]
	global_load_dwordx4 v[130:133], v[100:101], off
	v_lshl_add_u64 v[100:101], s[18:19], 0, v[98:99]
	global_load_dwordx4 v[118:121], v[100:101], off
	v_or_b32_e32 v98, 0x100, v98
	v_lshl_add_u64 v[100:101], s[46:47], 0, v[98:99]
	v_lshl_add_u64 v[98:99], s[18:19], 0, v[98:99]
	global_load_dwordx4 v[122:125], v[100:101], off
	global_load_dwordx4 v[114:117], v[98:99], off
	v_lshlrev_b64 v[98:99], 10, v[186:187]
	v_lshl_add_u64 v[126:127], v[98:99], 0, v[176:177]
	v_lshlrev_b64 v[98:99], 1, v[126:127]
	v_lshl_add_u64 v[100:101], s[46:47], 0, v[98:99]
	global_load_dwordx4 v[110:113], v[100:101], off
	v_lshl_add_u64 v[100:101], s[18:19], 0, v[98:99]
	global_load_dwordx4 v[106:109], v[100:101], off
	v_mul_f32_e64 v90, v207, -v95
	v_mul_f32_e32 v90, 0x3fb8aa3b, v90
	v_exp_f32_e32 v90, v90
	v_or_b32_e32 v98, 0x100, v98
	v_lshl_add_u64 v[100:101], s[46:47], 0, v[98:99]
	v_lshl_add_u64 v[98:99], s[18:19], 0, v[98:99]
	v_add_f32_e32 v90, 1.0, v90
	v_rcp_f32_e32 v95, v90
	v_mul_f32_e64 v90, v207, -v91
	v_mul_f32_e64 v91, v207, -v92
	v_mul_f32_e64 v92, v207, -v93
	v_mul_f32_e32 v90, 0x3fb8aa3b, v90
	v_mul_f32_e32 v91, 0x3fb8aa3b, v91
	v_mul_f32_e32 v92, 0x3fb8aa3b, v92
	v_exp_f32_e32 v90, v90
	v_exp_f32_e32 v91, v91
	v_exp_f32_e32 v92, v92
	global_load_dwordx4 v[102:105], v[100:101], off
	v_add_f32_e32 v90, 1.0, v90
	global_load_dwordx4 v[98:101], v[98:99], off
	v_add_f32_e32 v91, 1.0, v91
	v_add_f32_e32 v92, 1.0, v92
	v_rcp_f32_e32 v139, v90
	v_mul_f32_e64 v90, v207, -v96
	v_rcp_f32_e32 v96, v91
	v_mul_f32_e64 v91, v207, -v97
	v_rcp_f32_e32 v97, v92
	v_mul_f32_e32 v90, 0x3fb8aa3b, v90
	v_mul_f32_e32 v91, 0x3fb8aa3b, v91
	v_exp_f32_e32 v90, v90
	v_exp_f32_e32 v91, v91
	v_add_f32_e32 v70, 1.0, v70
	v_rcp_f32_e32 v70, v70
	v_add_f32_e32 v90, 1.0, v90
	v_add_f32_e32 v91, 1.0, v91
	v_rcp_f32_e32 v90, v90
	v_rcp_f32_e32 v91, v91
	v_mul_f32_e64 v58, v205, -v58
	v_mul_f32_e32 v58, 0x3fb8aa3b, v58
	v_exp_f32_e32 v58, v58
	v_mul_f32_e64 v50, v205, -v50
	v_mul_f32_e32 v50, 0x3fb8aa3b, v50
	v_exp_f32_e32 v50, v50
	v_add_f32_e32 v58, 1.0, v58
	v_mul_f32_e64 v62, v205, -v62
	v_mul_f32_e32 v62, 0x3fb8aa3b, v62
	v_add_f32_e32 v50, 1.0, v50
	v_exp_f32_e32 v62, v62
	v_mul_f32_e64 v54, v205, -v54
	v_mul_f32_e32 v54, 0x3fb8aa3b, v54
	v_exp_f32_e32 v54, v54
	v_add_f32_e32 v62, 1.0, v62
	v_mul_f32_e64 v42, v204, -v42
	v_rcp_f32_e32 v62, v62
	v_mul_f32_e32 v42, 0x3fb8aa3b, v42
	v_add_f32_e32 v54, 1.0, v54
	v_exp_f32_e32 v42, v42
	v_rcp_f32_e32 v54, v54
	v_mul_f32_e64 v34, v204, -v34
	v_mul_f32_e32 v34, 0x3fb8aa3b, v34
	v_add_f32_e32 v42, 1.0, v42
	v_exp_f32_e32 v34, v34
	v_mul_f32_e64 v46, v204, -v46
	v_mul_f32_e32 v46, 0x3fb8aa3b, v46
	v_exp_f32_e32 v46, v46
	s_waitcnt vmcnt(7)
	v_lshlrev_b32_e32 v136, 16, v132
	v_and_b32_e32 v137, 0xffff0000, v132
	v_lshlrev_b32_e32 v132, 16, v133
	v_and_b32_e32 v133, 0xffff0000, v133
	s_waitcnt vmcnt(6)
	v_lshlrev_b32_e32 v142, 16, v120
	v_and_b32_e32 v143, 0xffff0000, v120
	v_lshlrev_b32_e32 v120, 16, v121
	v_and_b32_e32 v121, 0xffff0000, v121
	v_pk_fma_f32 v[96:97], v[96:97], v[120:121], v[132:133]
	v_rcp_f32_e32 v120, v82
	v_mul_f32_e64 v82, v207, -v87
	v_mul_f32_e32 v82, 0x3fb8aa3b, v82
	v_exp_f32_e32 v82, v82
	v_lshlrev_b32_e32 v134, 16, v130
	v_and_b32_e32 v135, 0xffff0000, v130
	v_lshlrev_b32_e32 v130, 16, v131
	v_add_f32_e32 v82, 1.0, v82
	v_rcp_f32_e32 v87, v82
	v_mul_f32_e64 v82, v207, -v83
	v_mul_f32_e64 v83, v207, -v84
	v_mul_f32_e32 v82, 0x3fb8aa3b, v82
	v_mul_f32_e32 v83, 0x3fb8aa3b, v83
	v_exp_f32_e32 v82, v82
	v_exp_f32_e32 v83, v83
	v_mul_f32_e64 v84, v207, -v85
	v_mul_f32_e32 v84, 0x3fb8aa3b, v84
	v_add_f32_e32 v82, 1.0, v82
	v_add_f32_e32 v83, 1.0, v83
	v_rcp_f32_e32 v121, v82
	v_mul_f32_e64 v82, v207, -v88
	v_rcp_f32_e32 v88, v83
	v_mul_f32_e64 v83, v207, -v89
	v_mul_f32_e32 v82, 0x3fb8aa3b, v82
	v_mul_f32_e32 v83, 0x3fb8aa3b, v83
	v_exp_f32_e32 v82, v82
	v_exp_f32_e32 v83, v83
	v_exp_f32_e32 v84, v84
	v_and_b32_e32 v131, 0xffff0000, v131
	v_add_f32_e32 v82, 1.0, v82
	v_add_f32_e32 v83, 1.0, v83
	v_rcp_f32_e32 v82, v82
	v_rcp_f32_e32 v83, v83
	v_lshlrev_b32_e32 v140, 16, v118
	v_and_b32_e32 v141, 0xffff0000, v118
	v_lshlrev_b32_e32 v118, 16, v119
	v_and_b32_e32 v119, 0xffff0000, v119
	v_pk_fma_f32 v[92:93], v[90:91], v[118:119], v[130:131]
	v_pk_fma_f32 v[90:91], v[94:95], v[140:141], v[134:135]
	v_lshl_add_u64 v[118:119], v[128:129], 2, s[52:53]
	v_pk_fma_f32 v[94:95], v[138:139], v[142:143], v[136:137]
	global_store_dwordx4 v[118:119], v[90:93], off nt
	global_store_dwordx4 v[118:119], v[94:97], off offset:16 nt
	v_add_f32_e32 v84, 1.0, v84
	s_waitcnt vmcnt(7)
; __device__ __forceinline__ float bf_lo(unsigned w) { return __uint_as_float(w << 16); }
; __device__ __forceinline__ float bf_hi(unsigned w) { return __uint_as_float(w & 0xffff0000u); }
; __device__ __forceinline__ float dot4(f32x4 a) { return (a[0] * a[0] + a[1] * a[1]) + (a[2] * a[2] + a[3] * a[3]); }
; __device__ __forceinline__ u32x4 pack8(f32x4 a, f32x4 b) { u32x4 w; w.x = cvt_pk_bf16(a[0], a[1]); w.y = cvt_pk_bf16(a[2], a[3]); w.z = cvt_pk_bf16(b[0], b[1]); w.w = cvt_pk_bf16(b[2], b[3]); return w; }
;     __device__ __forceinline__ void operator()(const f32x4 (&acc)[2][2][4][2], const Unit& u, int wr, int wc, int fr, int fq) const {
;     ...
;             for (int k = 0; k < NB; ++k) {
;                 const int ai = (g * NB + k) >> 2, m = (g * NB + k) & 3;
;                 const int row = u.pm * 256 + ai * 128 + wr * 64 + m * 16 + fr;
;                 float ss = 0.f;
; #pragma unroll
;                 for (int bj = 0; bj < 2; ++bj) {
;                     const size_t off = (size_t)row * 1024 + colb + bj * 128;
;                     const u32x4 w = xw[k][bj];
;                     const f32x4 x0 = (f32x4){bf_lo(w.x), bf_hi(w.x), bf_lo(w.y), bf_hi(w.y)}, x1 = (f32x4){bf_lo(w.z), bf_hi(w.z), bf_lo(w.w), bf_hi(w.w)};
;                     f32x4 d0 = acc[ai][bj][m][0], d1 = acc[ai][bj][m][1];
;                     if (MODE == 2) { const float r2 = rs8[ai][m] * rs8[ai][m]; d0 = d0 * r2; d1 = d1 * r2; }
;                     if (MODE == 1) {
;                         const float rs = rs8[ai][m];
;                         const u32x4 q = pw[k][bj];
;                         const f32x4 p0 = (f32x4){bf_lo(q.x), bf_hi(q.x), bf_lo(q.y), bf_hi(q.y)}, p1 = (f32x4){bf_lo(q.z), bf_hi(q.z), bf_lo(q.w), bf_hi(q.w)};
; #pragma unroll
;                         for (int i = 0; i < 4; ++i) { d0[i] = p0[i] * __builtin_amdgcn_rcpf(1.0f + __expf(-d0[i] * rs)); d1[i] = p1[i] * __builtin_amdgcn_rcpf(1.0f + __expf(-d1[i] * rs)); }
;                     }
;                     const f32x4 y0 = x0 + d0, y1 = x1 + d1;
;                     if (LAST) { *(f32x4*)(xout + off) = y0; *(f32x4*)(xout + off + 4) = y1; }
;                     else { ss += dot4(y0) + dot4(y1); *(u32x4*)(xb + off) = pack8(y0, y1); }
	v_lshlrev_b32_e32 v90, 16, v122
	v_and_b32_e32 v91, 0xffff0000, v122
	v_lshlrev_b32_e32 v92, 16, v123
	v_and_b32_e32 v93, 0xffff0000, v123
	s_waitcnt vmcnt(6)
	v_lshlrev_b32_e32 v122, 16, v114
	v_and_b32_e32 v123, 0xffff0000, v114
	v_lshlrev_b32_e32 v114, 16, v115
	v_and_b32_e32 v115, 0xffff0000, v115
	v_rcp_f32_e32 v89, v84
	v_pk_fma_f32 v[84:85], v[82:83], v[114:115], v[92:93]
	v_pk_fma_f32 v[82:83], v[86:87], v[122:123], v[90:91]
	v_rcp_f32_e32 v90, v74
	v_mul_f32_e64 v74, v206, -v79
	v_mul_f32_e32 v74, 0x3fb8aa3b, v74
	v_exp_f32_e32 v74, v74
	v_lshlrev_b32_e32 v94, 16, v124
	v_and_b32_e32 v95, 0xffff0000, v124
	v_lshlrev_b32_e32 v96, 16, v125
	v_add_f32_e32 v74, 1.0, v74
	v_rcp_f32_e32 v79, v74
	v_mul_f32_e64 v74, v206, -v75
	v_mul_f32_e64 v75, v206, -v76
	v_mul_f32_e32 v74, 0x3fb8aa3b, v74
	v_mul_f32_e32 v75, 0x3fb8aa3b, v75
	v_exp_f32_e32 v74, v74
	v_exp_f32_e32 v75, v75
	v_mul_f32_e64 v76, v206, -v77
	v_mul_f32_e32 v76, 0x3fb8aa3b, v76
	v_add_f32_e32 v74, 1.0, v74
	v_add_f32_e32 v75, 1.0, v75
	v_rcp_f32_e32 v91, v74
	v_mul_f32_e64 v74, v206, -v80
	v_rcp_f32_e32 v80, v75
	v_mul_f32_e64 v75, v206, -v81
	v_mul_f32_e32 v74, 0x3fb8aa3b, v74
	v_mul_f32_e32 v75, 0x3fb8aa3b, v75
	v_exp_f32_e32 v74, v74
	v_exp_f32_e32 v75, v75
	v_exp_f32_e32 v76, v76
	v_and_b32_e32 v97, 0xffff0000, v125
	v_add_f32_e32 v74, 1.0, v74
	v_add_f32_e32 v75, 1.0, v75
	v_rcp_f32_e32 v74, v74
	v_rcp_f32_e32 v75, v75
	v_lshlrev_b32_e32 v124, 16, v116
	v_and_b32_e32 v125, 0xffff0000, v116
	v_lshlrev_b32_e32 v116, 16, v117
	v_and_b32_e32 v117, 0xffff0000, v117
	v_pk_fma_f32 v[88:89], v[88:89], v[116:117], v[96:97]
	v_pk_fma_f32 v[86:87], v[120:121], v[124:125], v[94:95]
	global_store_dwordx4 v[118:119], v[82:85], off offset:512 nt
	global_store_dwordx4 v[118:119], v[86:89], off offset:528 nt
	s_waitcnt vmcnt(6)
	v_lshlrev_b32_e32 v96, 16, v107
	v_lshlrev_b32_e32 v84, 16, v111
	v_and_b32_e32 v85, 0xffff0000, v111
	v_and_b32_e32 v97, 0xffff0000, v107
	v_add_f32_e32 v76, 1.0, v76
	v_rcp_f32_e32 v81, v76
	v_pk_fma_f32 v[76:77], v[74:75], v[96:97], v[84:85]
	v_rcp_f32_e32 v84, v66
	v_mul_f32_e64 v66, v206, -v71
	v_mul_f32_e32 v66, 0x3fb8aa3b, v66
	v_exp_f32_e32 v66, v66
	v_lshlrev_b32_e32 v82, 16, v110
	v_and_b32_e32 v83, 0xffff0000, v110
	v_lshlrev_b32_e32 v92, 16, v106
	v_add_f32_e32 v66, 1.0, v66
	v_rcp_f32_e32 v71, v66
	v_mul_f32_e64 v66, v206, -v67
	v_mul_f32_e64 v67, v206, -v68
	v_mul_f32_e32 v66, 0x3fb8aa3b, v66
	v_mul_f32_e32 v67, 0x3fb8aa3b, v67
	v_exp_f32_e32 v66, v66
	v_exp_f32_e32 v67, v67
	v_mul_f32_e64 v68, v206, -v69
	v_mul_f32_e32 v68, 0x3fb8aa3b, v68
	v_add_f32_e32 v66, 1.0, v66
	v_add_f32_e32 v67, 1.0, v67
	v_rcp_f32_e32 v85, v66
	v_mul_f32_e64 v66, v206, -v72
	v_rcp_f32_e32 v72, v67
	v_mul_f32_e64 v67, v206, -v73
	v_mul_f32_e32 v66, 0x3fb8aa3b, v66
	v_mul_f32_e32 v67, 0x3fb8aa3b, v67
	v_exp_f32_e32 v66, v66
	v_exp_f32_e32 v67, v67
	v_exp_f32_e32 v68, v68
	v_and_b32_e32 v93, 0xffff0000, v106
	v_add_f32_e32 v66, 1.0, v66
	v_add_f32_e32 v67, 1.0, v67
	v_rcp_f32_e32 v66, v66
	v_rcp_f32_e32 v67, v67
	v_add_f32_e32 v68, 1.0, v68
	v_rcp_f32_e32 v73, v68
	v_lshlrev_b32_e32 v86, 16, v112
	v_and_b32_e32 v87, 0xffff0000, v112
	v_lshlrev_b32_e32 v88, 16, v113
	v_and_b32_e32 v89, 0xffff0000, v113
	v_lshlrev_b32_e32 v94, 16, v108
	v_and_b32_e32 v95, 0xffff0000, v108
	v_lshlrev_b32_e32 v106, 16, v109
	v_and_b32_e32 v107, 0xffff0000, v109
	v_pk_fma_f32 v[74:75], v[78:79], v[92:93], v[82:83]
	v_lshl_add_u64 v[82:83], v[126:127], 2, s[52:53]
	v_pk_fma_f32 v[80:81], v[80:81], v[106:107], v[88:89]
	v_pk_fma_f32 v[78:79], v[90:91], v[94:95], v[86:87]
	global_store_dwordx4 v[82:83], v[74:77], off nt
	global_store_dwordx4 v[82:83], v[78:81], off offset:16 nt
	s_waitcnt vmcnt(6)
	v_lshlrev_b32_e32 v86, 16, v98
	v_lshlrev_b32_e32 v74, 16, v102
	v_and_b32_e32 v75, 0xffff0000, v102
	v_lshlrev_b32_e32 v76, 16, v103
	v_and_b32_e32 v77, 0xffff0000, v103
	v_and_b32_e32 v87, 0xffff0000, v98
	v_lshlrev_b32_e32 v90, 16, v99
	v_and_b32_e32 v91, 0xffff0000, v99
	v_lshlrev_b32_e32 v78, 16, v104
	v_and_b32_e32 v79, 0xffff0000, v104
	v_lshlrev_b32_e32 v80, 16, v105
	v_and_b32_e32 v81, 0xffff0000, v105
	v_lshlrev_b32_e32 v88, 16, v100
	v_and_b32_e32 v89, 0xffff0000, v100
	v_lshlrev_b32_e32 v92, 16, v101
	v_and_b32_e32 v93, 0xffff0000, v101
	v_pk_fma_f32 v[68:69], v[66:67], v[90:91], v[76:77]
	v_pk_fma_f32 v[66:67], v[70:71], v[86:87], v[74:75]
	v_pk_fma_f32 v[72:73], v[72:73], v[92:93], v[80:81]
	v_pk_fma_f32 v[70:71], v[84:85], v[88:89], v[78:79]
	global_store_dwordx4 v[82:83], v[66:69], off offset:512 nt
	global_store_dwordx4 v[82:83], v[70:73], off offset:528 nt
	v_rcp_f32_e32 v106, v58
	v_lshlrev_b64 v[66:67], 10, v[184:185]
	v_lshl_add_u64 v[96:97], v[66:67], 0, v[176:177]
	v_lshlrev_b64 v[66:67], 1, v[96:97]
	v_lshl_add_u64 v[68:69], s[46:47], 0, v[66:67]
	global_load_dwordx4 v[98:101], v[68:69], off
	v_lshl_add_u64 v[68:69], s[18:19], 0, v[66:67]
	global_load_dwordx4 v[86:89], v[68:69], off
	v_or_b32_e32 v66, 0x100, v66
	v_lshl_add_u64 v[68:69], s[46:47], 0, v[66:67]
	v_lshl_add_u64 v[66:67], s[18:19], 0, v[66:67]
	global_load_dwordx4 v[90:93], v[68:69], off
	global_load_dwordx4 v[82:85], v[66:67], off
	v_lshlrev_b64 v[66:67], 10, v[182:183]
	v_lshl_add_u64 v[94:95], v[66:67], 0, v[176:177]
	v_lshlrev_b64 v[66:67], 1, v[94:95]
	v_lshl_add_u64 v[68:69], s[46:47], 0, v[66:67]
	global_load_dwordx4 v[78:81], v[68:69], off
	v_lshl_add_u64 v[68:69], s[18:19], 0, v[66:67]
	global_load_dwordx4 v[74:77], v[68:69], off
	v_mul_f32_e64 v58, v205, -v63
	v_mul_f32_e32 v58, 0x3fb8aa3b, v58
	v_exp_f32_e32 v58, v58
	v_or_b32_e32 v66, 0x100, v66
	v_lshl_add_u64 v[68:69], s[46:47], 0, v[66:67]
; __device__ __forceinline__ float bf_lo(unsigned w) { return __uint_as_float(w << 16); }
; __device__ __forceinline__ float bf_hi(unsigned w) { return __uint_as_float(w & 0xffff0000u); }
; __device__ __forceinline__ float dot4(f32x4 a) { return (a[0] * a[0] + a[1] * a[1]) + (a[2] * a[2] + a[3] * a[3]); }
; __device__ __forceinline__ u32x4 pack8(f32x4 a, f32x4 b) { u32x4 w; w.x = cvt_pk_bf16(a[0], a[1]); w.y = cvt_pk_bf16(a[2], a[3]); w.z = cvt_pk_bf16(b[0], b[1]); w.w = cvt_pk_bf16(b[2], b[3]); return w; }
;     __device__ __forceinline__ void operator()(const f32x4 (&acc)[2][2][4][2], const Unit& u, int wr, int wc, int fr, int fq) const {
;     ...
;             for (int k = 0; k < NB; ++k) {
;                 const int ai = (g * NB + k) >> 2, m = (g * NB + k) & 3;
;                 const int row = u.pm * 256 + ai * 128 + wr * 64 + m * 16 + fr;
;                 float ss = 0.f;
; #pragma unroll
;                 for (int bj = 0; bj < 2; ++bj) {
;                     const size_t off = (size_t)row * 1024 + colb + bj * 128;
;                     const u32x4 w = xw[k][bj];
;                     const f32x4 x0 = (f32x4){bf_lo(w.x), bf_hi(w.x), bf_lo(w.y), bf_hi(w.y)}, x1 = (f32x4){bf_lo(w.z), bf_hi(w.z), bf_lo(w.w), bf_hi(w.w)};
;                     f32x4 d0 = acc[ai][bj][m][0], d1 = acc[ai][bj][m][1];
;                     if (MODE == 2) { const float r2 = rs8[ai][m] * rs8[ai][m]; d0 = d0 * r2; d1 = d1 * r2; }
;                     if (MODE == 1) {
;                         const float rs = rs8[ai][m];
;                         const u32x4 q = pw[k][bj];
;                         const f32x4 p0 = (f32x4){bf_lo(q.x), bf_hi(q.x), bf_lo(q.y), bf_hi(q.y)}, p1 = (f32x4){bf_lo(q.z), bf_hi(q.z), bf_lo(q.w), bf_hi(q.w)};
; #pragma unroll
;                         for (int i = 0; i < 4; ++i) { d0[i] = p0[i] * __builtin_amdgcn_rcpf(1.0f + __expf(-d0[i] * rs)); d1[i] = p1[i] * __builtin_amdgcn_rcpf(1.0f + __expf(-d1[i] * rs)); }
;                     }
;                     const f32x4 y0 = x0 + d0, y1 = x1 + d1;
;                     if (LAST) { *(f32x4*)(xout + off) = y0; *(f32x4*)(xout + off + 4) = y1; }
;                     else { ss += dot4(y0) + dot4(y1); *(u32x4*)(xb + off) = pack8(y0, y1); }
	v_lshl_add_u64 v[66:67], s[18:19], 0, v[66:67]
	v_add_f32_e32 v58, 1.0, v58
	v_rcp_f32_e32 v63, v58
	v_mul_f32_e64 v58, v205, -v59
	v_mul_f32_e64 v59, v205, -v60
	v_mul_f32_e64 v60, v205, -v61
	v_mul_f32_e32 v58, 0x3fb8aa3b, v58
	v_mul_f32_e32 v59, 0x3fb8aa3b, v59
	v_mul_f32_e32 v60, 0x3fb8aa3b, v60
	v_exp_f32_e32 v58, v58
	v_exp_f32_e32 v59, v59
	v_exp_f32_e32 v60, v60
	global_load_dwordx4 v[70:73], v[68:69], off
	v_add_f32_e32 v58, 1.0, v58
	global_load_dwordx4 v[66:69], v[66:67], off
	v_add_f32_e32 v59, 1.0, v59
	v_add_f32_e32 v60, 1.0, v60
	v_rcp_f32_e32 v107, v58
	v_mul_f32_e64 v58, v205, -v64
	v_rcp_f32_e32 v64, v59
	v_mul_f32_e64 v59, v205, -v65
	v_rcp_f32_e32 v65, v60
	v_mul_f32_e32 v58, 0x3fb8aa3b, v58
	v_mul_f32_e32 v59, 0x3fb8aa3b, v59
	v_exp_f32_e32 v58, v58
	v_exp_f32_e32 v59, v59
	v_add_f32_e32 v34, 1.0, v34
	v_mul_f32_e64 v38, v204, -v38
	v_add_f32_e32 v58, 1.0, v58
	v_add_f32_e32 v59, 1.0, v59
	v_rcp_f32_e32 v58, v58
	v_rcp_f32_e32 v59, v59
	v_mul_f32_e32 v38, 0x3fb8aa3b, v38
	v_exp_f32_e32 v38, v38
	v_add_f32_e32 v46, 1.0, v46
	v_rcp_f32_e32 v46, v46
	v_mul_f32_e64 v26, v203, -v26
	v_add_f32_e32 v38, 1.0, v38
	v_rcp_f32_e32 v38, v38
	v_mul_f32_e32 v26, 0x3fb8aa3b, v26
	v_exp_f32_e32 v26, v26
	v_mul_f32_e64 v18, v203, -v18
	v_mul_f32_e32 v18, 0x3fb8aa3b, v18
	v_exp_f32_e32 v18, v18
	v_add_f32_e32 v26, 1.0, v26
	v_mul_f32_e64 v30, v203, -v30
	v_mul_f32_e32 v30, 0x3fb8aa3b, v30
	v_add_f32_e32 v18, 1.0, v18
	v_exp_f32_e32 v30, v30
	v_mul_f32_e64 v22, v203, -v22
	v_mul_f32_e32 v22, 0x3fb8aa3b, v22
	v_exp_f32_e32 v22, v22
	v_add_f32_e32 v30, 1.0, v30
	v_mul_f32_e64 v10, v202, -v10
	v_rcp_f32_e32 v30, v30
	v_mul_f32_e32 v10, 0x3fb8aa3b, v10
	v_add_f32_e32 v22, 1.0, v22
	v_exp_f32_e32 v10, v10
	v_rcp_f32_e32 v22, v22
	v_mul_f32_e64 v2, v202, -v2
	s_waitcnt vmcnt(7)
	v_lshlrev_b32_e32 v104, 16, v100
	v_and_b32_e32 v105, 0xffff0000, v100
	v_lshlrev_b32_e32 v100, 16, v101
	v_and_b32_e32 v101, 0xffff0000, v101
	s_waitcnt vmcnt(6)
	v_lshlrev_b32_e32 v110, 16, v88
	v_and_b32_e32 v111, 0xffff0000, v88
	v_lshlrev_b32_e32 v88, 16, v89
	v_and_b32_e32 v89, 0xffff0000, v89
	v_pk_fma_f32 v[64:65], v[64:65], v[88:89], v[100:101]
	v_rcp_f32_e32 v88, v50
	v_mul_f32_e64 v50, v205, -v55
	v_mul_f32_e32 v50, 0x3fb8aa3b, v50
	v_exp_f32_e32 v50, v50
	v_lshlrev_b32_e32 v102, 16, v98
	v_and_b32_e32 v103, 0xffff0000, v98
	v_lshlrev_b32_e32 v98, 16, v99
	v_add_f32_e32 v50, 1.0, v50
	v_rcp_f32_e32 v55, v50
	v_mul_f32_e64 v50, v205, -v51
	v_mul_f32_e64 v51, v205, -v52
	v_mul_f32_e32 v50, 0x3fb8aa3b, v50
	v_mul_f32_e32 v51, 0x3fb8aa3b, v51
	v_exp_f32_e32 v50, v50
	v_exp_f32_e32 v51, v51
	v_mul_f32_e64 v52, v205, -v53
	v_mul_f32_e32 v52, 0x3fb8aa3b, v52
	v_add_f32_e32 v50, 1.0, v50
	v_add_f32_e32 v51, 1.0, v51
	v_rcp_f32_e32 v89, v50
	v_mul_f32_e64 v50, v205, -v56
	v_rcp_f32_e32 v56, v51
	v_mul_f32_e64 v51, v205, -v57
	v_mul_f32_e32 v50, 0x3fb8aa3b, v50
	v_mul_f32_e32 v51, 0x3fb8aa3b, v51
	v_exp_f32_e32 v50, v50
	v_exp_f32_e32 v51, v51
	v_exp_f32_e32 v52, v52
	v_and_b32_e32 v99, 0xffff0000, v99
	v_add_f32_e32 v50, 1.0, v50
	v_add_f32_e32 v51, 1.0, v51
	v_rcp_f32_e32 v50, v50
	v_rcp_f32_e32 v51, v51
	v_lshlrev_b32_e32 v108, 16, v86
	v_and_b32_e32 v109, 0xffff0000, v86
	v_lshlrev_b32_e32 v86, 16, v87
	v_and_b32_e32 v87, 0xffff0000, v87
	v_pk_fma_f32 v[60:61], v[58:59], v[86:87], v[98:99]
	v_pk_fma_f32 v[58:59], v[62:63], v[108:109], v[102:103]
	v_lshl_add_u64 v[86:87], v[96:97], 2, s[52:53]
	v_pk_fma_f32 v[62:63], v[106:107], v[110:111], v[104:105]
	global_store_dwordx4 v[86:87], v[58:61], off nt
	global_store_dwordx4 v[86:87], v[62:65], off offset:16 nt
	v_add_f32_e32 v52, 1.0, v52
	s_waitcnt vmcnt(7)
	v_lshlrev_b32_e32 v58, 16, v90
	v_and_b32_e32 v59, 0xffff0000, v90
	v_lshlrev_b32_e32 v60, 16, v91
	v_and_b32_e32 v61, 0xffff0000, v91
	s_waitcnt vmcnt(6)
	v_lshlrev_b32_e32 v90, 16, v82
	v_and_b32_e32 v91, 0xffff0000, v82
	v_lshlrev_b32_e32 v82, 16, v83
	v_and_b32_e32 v83, 0xffff0000, v83
	v_rcp_f32_e32 v57, v52
	v_pk_fma_f32 v[52:53], v[50:51], v[82:83], v[60:61]
	v_pk_fma_f32 v[50:51], v[54:55], v[90:91], v[58:59]
	v_rcp_f32_e32 v58, v42
	v_mul_f32_e64 v42, v204, -v47
	v_mul_f32_e32 v42, 0x3fb8aa3b, v42
	v_exp_f32_e32 v42, v42
	v_lshlrev_b32_e32 v62, 16, v92
	v_and_b32_e32 v63, 0xffff0000, v92
	v_lshlrev_b32_e32 v64, 16, v93
	v_add_f32_e32 v42, 1.0, v42
	v_rcp_f32_e32 v47, v42
	v_mul_f32_e64 v42, v204, -v43
	v_mul_f32_e64 v43, v204, -v44
	v_mul_f32_e32 v42, 0x3fb8aa3b, v42
	v_mul_f32_e32 v43, 0x3fb8aa3b, v43
	v_exp_f32_e32 v42, v42
	v_exp_f32_e32 v43, v43
	v_mul_f32_e64 v44, v204, -v45
	v_mul_f32_e32 v44, 0x3fb8aa3b, v44
	v_add_f32_e32 v42, 1.0, v42
	v_add_f32_e32 v43, 1.0, v43
	v_rcp_f32_e32 v59, v42
	v_mul_f32_e64 v42, v204, -v48
	v_rcp_f32_e32 v48, v43
	v_mul_f32_e64 v43, v204, -v49
	v_mul_f32_e32 v42, 0x3fb8aa3b, v42
	v_mul_f32_e32 v43, 0x3fb8aa3b, v43
	v_exp_f32_e32 v42, v42
	v_exp_f32_e32 v43, v43
	v_exp_f32_e32 v44, v44
	v_and_b32_e32 v65, 0xffff0000, v93
	v_add_f32_e32 v42, 1.0, v42
	v_add_f32_e32 v43, 1.0, v43
	v_rcp_f32_e32 v42, v42
	v_rcp_f32_e32 v43, v43
	v_lshlrev_b32_e32 v92, 16, v84
	v_and_b32_e32 v93, 0xffff0000, v84
	v_lshlrev_b32_e32 v84, 16, v85
	v_and_b32_e32 v85, 0xffff0000, v85
	v_pk_fma_f32 v[56:57], v[56:57], v[84:85], v[64:65]
	v_pk_fma_f32 v[54:55], v[88:89], v[92:93], v[62:63]
	global_store_dwordx4 v[86:87], v[50:53], off offset:512 nt
	global_store_dwordx4 v[86:87], v[54:57], off offset:528 nt
	s_waitcnt vmcnt(6)
; __device__ __forceinline__ float bf_lo(unsigned w) { return __uint_as_float(w << 16); }
; __device__ __forceinline__ float bf_hi(unsigned w) { return __uint_as_float(w & 0xffff0000u); }
; __device__ __forceinline__ float dot4(f32x4 a) { return (a[0] * a[0] + a[1] * a[1]) + (a[2] * a[2] + a[3] * a[3]); }
; __device__ __forceinline__ u32x4 pack8(f32x4 a, f32x4 b) { u32x4 w; w.x = cvt_pk_bf16(a[0], a[1]); w.y = cvt_pk_bf16(a[2], a[3]); w.z = cvt_pk_bf16(b[0], b[1]); w.w = cvt_pk_bf16(b[2], b[3]); return w; }
;     __device__ __forceinline__ void operator()(const f32x4 (&acc)[2][2][4][2], const Unit& u, int wr, int wc, int fr, int fq) const {
;     ...
;             for (int k = 0; k < NB; ++k) {
;                 const int ai = (g * NB + k) >> 2, m = (g * NB + k) & 3;
;                 const int row = u.pm * 256 + ai * 128 + wr * 64 + m * 16 + fr;
;                 float ss = 0.f;
; #pragma unroll
;                 for (int bj = 0; bj < 2; ++bj) {
;                     const size_t off = (size_t)row * 1024 + colb + bj * 128;
;                     const u32x4 w = xw[k][bj];
;                     const f32x4 x0 = (f32x4){bf_lo(w.x), bf_hi(w.x), bf_lo(w.y), bf_hi(w.y)}, x1 = (f32x4){bf_lo(w.z), bf_hi(w.z), bf_lo(w.w), bf_hi(w.w)};
;                     f32x4 d0 = acc[ai][bj][m][0], d1 = acc[ai][bj][m][1];
;                     if (MODE == 2) { const float r2 = rs8[ai][m] * rs8[ai][m]; d0 = d0 * r2; d1 = d1 * r2; }
;                     if (MODE == 1) {
;                         const float rs = rs8[ai][m];
;                         const u32x4 q = pw[k][bj];
;                         const f32x4 p0 = (f32x4){bf_lo(q.x), bf_hi(q.x), bf_lo(q.y), bf_hi(q.y)}, p1 = (f32x4){bf_lo(q.z), bf_hi(q.z), bf_lo(q.w), bf_hi(q.w)};
; #pragma unroll
;                         for (int i = 0; i < 4; ++i) { d0[i] = p0[i] * __builtin_amdgcn_rcpf(1.0f + __expf(-d0[i] * rs)); d1[i] = p1[i] * __builtin_amdgcn_rcpf(1.0f + __expf(-d1[i] * rs)); }
;                     }
;                     const f32x4 y0 = x0 + d0, y1 = x1 + d1;
;                     if (LAST) { *(f32x4*)(xout + off) = y0; *(f32x4*)(xout + off + 4) = y1; }
;                     else { ss += dot4(y0) + dot4(y1); *(u32x4*)(xb + off) = pack8(y0, y1); }
	v_lshlrev_b32_e32 v64, 16, v75
	v_lshlrev_b32_e32 v52, 16, v79
	v_and_b32_e32 v53, 0xffff0000, v79
	v_and_b32_e32 v65, 0xffff0000, v75
	v_add_f32_e32 v44, 1.0, v44
	v_rcp_f32_e32 v49, v44
	v_pk_fma_f32 v[44:45], v[42:43], v[64:65], v[52:53]
	v_rcp_f32_e32 v52, v34
	v_mul_f32_e64 v34, v204, -v39
	v_mul_f32_e32 v34, 0x3fb8aa3b, v34
	v_exp_f32_e32 v34, v34
	v_lshlrev_b32_e32 v50, 16, v78
	v_and_b32_e32 v51, 0xffff0000, v78
	v_lshlrev_b32_e32 v60, 16, v74
	v_add_f32_e32 v34, 1.0, v34
	v_rcp_f32_e32 v39, v34
	v_mul_f32_e64 v34, v204, -v35
	v_mul_f32_e64 v35, v204, -v36
	v_mul_f32_e32 v34, 0x3fb8aa3b, v34
	v_mul_f32_e32 v35, 0x3fb8aa3b, v35
	v_exp_f32_e32 v34, v34
	v_exp_f32_e32 v35, v35
	v_mul_f32_e64 v36, v204, -v37
	v_mul_f32_e32 v36, 0x3fb8aa3b, v36
	v_add_f32_e32 v34, 1.0, v34
	v_add_f32_e32 v35, 1.0, v35
	v_rcp_f32_e32 v53, v34
	v_mul_f32_e64 v34, v204, -v40
	v_rcp_f32_e32 v40, v35
	v_mul_f32_e64 v35, v204, -v41
	v_mul_f32_e32 v34, 0x3fb8aa3b, v34
	v_mul_f32_e32 v35, 0x3fb8aa3b, v35
	v_exp_f32_e32 v34, v34
	v_exp_f32_e32 v35, v35
	v_exp_f32_e32 v36, v36
	v_and_b32_e32 v61, 0xffff0000, v74
	v_add_f32_e32 v34, 1.0, v34
	v_add_f32_e32 v35, 1.0, v35
	v_rcp_f32_e32 v34, v34
	v_rcp_f32_e32 v35, v35
	v_add_f32_e32 v36, 1.0, v36
	v_rcp_f32_e32 v41, v36
	v_lshlrev_b32_e32 v54, 16, v80
	v_and_b32_e32 v55, 0xffff0000, v80
	v_lshlrev_b32_e32 v56, 16, v81
	v_and_b32_e32 v57, 0xffff0000, v81
	v_lshlrev_b32_e32 v62, 16, v76
	v_and_b32_e32 v63, 0xffff0000, v76
	v_lshlrev_b32_e32 v74, 16, v77
	v_and_b32_e32 v75, 0xffff0000, v77
	v_pk_fma_f32 v[42:43], v[46:47], v[60:61], v[50:51]
	v_lshl_add_u64 v[50:51], v[94:95], 2, s[52:53]
	v_pk_fma_f32 v[48:49], v[48:49], v[74:75], v[56:57]
	v_pk_fma_f32 v[46:47], v[58:59], v[62:63], v[54:55]
	global_store_dwordx4 v[50:51], v[42:45], off nt
	global_store_dwordx4 v[50:51], v[46:49], off offset:16 nt
	s_waitcnt vmcnt(6)
	v_lshlrev_b32_e32 v54, 16, v66
	v_lshlrev_b32_e32 v42, 16, v70
	v_and_b32_e32 v43, 0xffff0000, v70
	v_lshlrev_b32_e32 v44, 16, v71
	v_and_b32_e32 v45, 0xffff0000, v71
	v_and_b32_e32 v55, 0xffff0000, v66
	v_lshlrev_b32_e32 v58, 16, v67
	v_and_b32_e32 v59, 0xffff0000, v67
	v_lshlrev_b32_e32 v46, 16, v72
	v_and_b32_e32 v47, 0xffff0000, v72
	v_lshlrev_b32_e32 v48, 16, v73
	v_and_b32_e32 v49, 0xffff0000, v73
	v_lshlrev_b32_e32 v56, 16, v68
	v_and_b32_e32 v57, 0xffff0000, v68
	v_lshlrev_b32_e32 v60, 16, v69
	v_and_b32_e32 v61, 0xffff0000, v69
	v_pk_fma_f32 v[36:37], v[34:35], v[58:59], v[44:45]
	v_pk_fma_f32 v[34:35], v[38:39], v[54:55], v[42:43]
	v_pk_fma_f32 v[40:41], v[40:41], v[60:61], v[48:49]
	v_pk_fma_f32 v[38:39], v[52:53], v[56:57], v[46:47]
	global_store_dwordx4 v[50:51], v[34:37], off offset:512 nt
	global_store_dwordx4 v[50:51], v[38:41], off offset:528 nt
	v_rcp_f32_e32 v74, v26
	v_lshlrev_b64 v[34:35], 10, v[180:181]
	v_lshl_add_u64 v[64:65], v[34:35], 0, v[176:177]
	v_lshlrev_b64 v[34:35], 1, v[64:65]
	v_lshl_add_u64 v[36:37], s[46:47], 0, v[34:35]
	global_load_dwordx4 v[66:69], v[36:37], off
	v_lshl_add_u64 v[36:37], s[18:19], 0, v[34:35]
	global_load_dwordx4 v[54:57], v[36:37], off
	v_or_b32_e32 v34, 0x100, v34
	v_lshl_add_u64 v[36:37], s[46:47], 0, v[34:35]
	v_lshl_add_u64 v[34:35], s[18:19], 0, v[34:35]
	global_load_dwordx4 v[58:61], v[36:37], off
	global_load_dwordx4 v[50:53], v[34:35], off
	v_lshlrev_b64 v[34:35], 10, v[178:179]
	v_lshl_add_u64 v[62:63], v[34:35], 0, v[176:177]
	v_lshlrev_b64 v[34:35], 1, v[62:63]
	v_lshl_add_u64 v[36:37], s[46:47], 0, v[34:35]
	global_load_dwordx4 v[46:49], v[36:37], off
	v_lshl_add_u64 v[36:37], s[18:19], 0, v[34:35]
	global_load_dwordx4 v[42:45], v[36:37], off
	v_mul_f32_e64 v26, v203, -v31
	v_mul_f32_e32 v26, 0x3fb8aa3b, v26
	v_exp_f32_e32 v26, v26
	v_or_b32_e32 v34, 0x100, v34
	v_lshl_add_u64 v[36:37], s[46:47], 0, v[34:35]
	v_lshl_add_u64 v[34:35], s[18:19], 0, v[34:35]
	v_add_f32_e32 v26, 1.0, v26
	v_rcp_f32_e32 v31, v26
	v_mul_f32_e64 v26, v203, -v27
	v_mul_f32_e64 v27, v203, -v28
	v_mul_f32_e64 v28, v203, -v29
	v_mul_f32_e32 v26, 0x3fb8aa3b, v26
	v_mul_f32_e32 v27, 0x3fb8aa3b, v27
	v_mul_f32_e32 v28, 0x3fb8aa3b, v28
	v_exp_f32_e32 v26, v26
	v_exp_f32_e32 v27, v27
	v_exp_f32_e32 v28, v28
	global_load_dwordx4 v[38:41], v[36:37], off
	v_add_f32_e32 v26, 1.0, v26
	global_load_dwordx4 v[34:37], v[34:35], off
	v_add_f32_e32 v27, 1.0, v27
	v_add_f32_e32 v28, 1.0, v28
	v_rcp_f32_e32 v75, v26
	v_mul_f32_e64 v26, v203, -v32
	v_rcp_f32_e32 v32, v27
	v_mul_f32_e64 v27, v203, -v33
	v_rcp_f32_e32 v33, v28
	v_mul_f32_e32 v26, 0x3fb8aa3b, v26
	v_mul_f32_e32 v27, 0x3fb8aa3b, v27
	v_exp_f32_e32 v26, v26
	v_exp_f32_e32 v27, v27
	v_add_f32_e32 v10, 1.0, v10
	v_mul_f32_e32 v2, 0x3fb8aa3b, v2
	v_add_f32_e32 v26, 1.0, v26
	v_add_f32_e32 v27, 1.0, v27
	v_rcp_f32_e32 v26, v26
	v_rcp_f32_e32 v27, v27
	v_exp_f32_e32 v2, v2
	v_mul_f32_e64 v14, v202, -v14
	v_mul_f32_e32 v14, 0x3fb8aa3b, v14
	v_exp_f32_e32 v14, v14
	v_add_f32_e32 v2, 1.0, v2
	v_mul_f32_e64 v6, v202, -v6
	v_mul_f32_e32 v6, 0x3fb8aa3b, v6
	v_exp_f32_e32 v6, v6
	v_add_f32_e32 v14, 1.0, v14
	v_rcp_f32_e32 v14, v14
	s_andn2_b64 vcc, exec, s[40:41]
	v_add_f32_e32 v6, 1.0, v6
	v_rcp_f32_e32 v6, v6
	s_waitcnt vmcnt(7)
	v_lshlrev_b32_e32 v72, 16, v68
	v_and_b32_e32 v73, 0xffff0000, v68
	v_lshlrev_b32_e32 v68, 16, v69
	v_and_b32_e32 v69, 0xffff0000, v69
	s_waitcnt vmcnt(6)
; __device__ __forceinline__ float bf_lo(unsigned w) { return __uint_as_float(w << 16); }
; __device__ __forceinline__ float bf_hi(unsigned w) { return __uint_as_float(w & 0xffff0000u); }
; __device__ __forceinline__ float dot4(f32x4 a) { return (a[0] * a[0] + a[1] * a[1]) + (a[2] * a[2] + a[3] * a[3]); }
; __device__ __forceinline__ u32x4 pack8(f32x4 a, f32x4 b) { u32x4 w; w.x = cvt_pk_bf16(a[0], a[1]); w.y = cvt_pk_bf16(a[2], a[3]); w.z = cvt_pk_bf16(b[0], b[1]); w.w = cvt_pk_bf16(b[2], b[3]); return w; }
;     __device__ __forceinline__ void operator()(const f32x4 (&acc)[2][2][4][2], const Unit& u, int wr, int wc, int fr, int fq) const {
;     ...
;             for (int k = 0; k < NB; ++k) {
;                 const int ai = (g * NB + k) >> 2, m = (g * NB + k) & 3;
;                 const int row = u.pm * 256 + ai * 128 + wr * 64 + m * 16 + fr;
;                 float ss = 0.f;
; #pragma unroll
;                 for (int bj = 0; bj < 2; ++bj) {
;                     const size_t off = (size_t)row * 1024 + colb + bj * 128;
;                     const u32x4 w = xw[k][bj];
;                     const f32x4 x0 = (f32x4){bf_lo(w.x), bf_hi(w.x), bf_lo(w.y), bf_hi(w.y)}, x1 = (f32x4){bf_lo(w.z), bf_hi(w.z), bf_lo(w.w), bf_hi(w.w)};
;                     f32x4 d0 = acc[ai][bj][m][0], d1 = acc[ai][bj][m][1];
;                     if (MODE == 2) { const float r2 = rs8[ai][m] * rs8[ai][m]; d0 = d0 * r2; d1 = d1 * r2; }
;                     if (MODE == 1) {
;                         const float rs = rs8[ai][m];
;                         const u32x4 q = pw[k][bj];
;                         const f32x4 p0 = (f32x4){bf_lo(q.x), bf_hi(q.x), bf_lo(q.y), bf_hi(q.y)}, p1 = (f32x4){bf_lo(q.z), bf_hi(q.z), bf_lo(q.w), bf_hi(q.w)};
; #pragma unroll
;                         for (int i = 0; i < 4; ++i) { d0[i] = p0[i] * __builtin_amdgcn_rcpf(1.0f + __expf(-d0[i] * rs)); d1[i] = p1[i] * __builtin_amdgcn_rcpf(1.0f + __expf(-d1[i] * rs)); }
;                     }
;                     const f32x4 y0 = x0 + d0, y1 = x1 + d1;
;                     if (LAST) { *(f32x4*)(xout + off) = y0; *(f32x4*)(xout + off + 4) = y1; }
;                     else { ss += dot4(y0) + dot4(y1); *(u32x4*)(xb + off) = pack8(y0, y1); }
	v_lshlrev_b32_e32 v78, 16, v56
	v_and_b32_e32 v79, 0xffff0000, v56
	v_lshlrev_b32_e32 v56, 16, v57
	v_and_b32_e32 v57, 0xffff0000, v57
	v_pk_fma_f32 v[32:33], v[32:33], v[56:57], v[68:69]
	v_rcp_f32_e32 v56, v18
	v_mul_f32_e64 v18, v203, -v23
	v_mul_f32_e32 v18, 0x3fb8aa3b, v18
	v_exp_f32_e32 v18, v18
	v_lshlrev_b32_e32 v70, 16, v66
	v_and_b32_e32 v71, 0xffff0000, v66
	v_lshlrev_b32_e32 v66, 16, v67
	v_add_f32_e32 v18, 1.0, v18
	v_rcp_f32_e32 v23, v18
	v_mul_f32_e64 v18, v203, -v19
	v_mul_f32_e64 v19, v203, -v20
	v_mul_f32_e32 v18, 0x3fb8aa3b, v18
	v_mul_f32_e32 v19, 0x3fb8aa3b, v19
	v_exp_f32_e32 v18, v18
	v_exp_f32_e32 v19, v19
	v_mul_f32_e64 v20, v203, -v21
	v_mul_f32_e32 v20, 0x3fb8aa3b, v20
	v_add_f32_e32 v18, 1.0, v18
	v_add_f32_e32 v19, 1.0, v19
	v_rcp_f32_e32 v57, v18
	v_mul_f32_e64 v18, v203, -v24
	v_rcp_f32_e32 v24, v19
	v_mul_f32_e64 v19, v203, -v25
	v_mul_f32_e32 v18, 0x3fb8aa3b, v18
	v_mul_f32_e32 v19, 0x3fb8aa3b, v19
	v_exp_f32_e32 v18, v18
	v_exp_f32_e32 v19, v19
	v_exp_f32_e32 v20, v20
	v_and_b32_e32 v67, 0xffff0000, v67
	v_add_f32_e32 v18, 1.0, v18
	v_add_f32_e32 v19, 1.0, v19
	v_rcp_f32_e32 v18, v18
	v_rcp_f32_e32 v19, v19
	v_lshlrev_b32_e32 v76, 16, v54
	v_and_b32_e32 v77, 0xffff0000, v54
	v_lshlrev_b32_e32 v54, 16, v55
	v_and_b32_e32 v55, 0xffff0000, v55
	v_pk_fma_f32 v[28:29], v[26:27], v[54:55], v[66:67]
	v_pk_fma_f32 v[26:27], v[30:31], v[76:77], v[70:71]
	v_lshl_add_u64 v[54:55], v[64:65], 2, s[52:53]
	v_pk_fma_f32 v[30:31], v[74:75], v[78:79], v[72:73]
	global_store_dwordx4 v[54:55], v[26:29], off nt
	global_store_dwordx4 v[54:55], v[30:33], off offset:16 nt
	v_add_f32_e32 v20, 1.0, v20
	s_waitcnt vmcnt(7)
	v_lshlrev_b32_e32 v26, 16, v58
	v_and_b32_e32 v27, 0xffff0000, v58
	v_lshlrev_b32_e32 v28, 16, v59
	v_and_b32_e32 v29, 0xffff0000, v59
	s_waitcnt vmcnt(6)
	v_lshlrev_b32_e32 v58, 16, v50
	v_and_b32_e32 v59, 0xffff0000, v50
	v_lshlrev_b32_e32 v50, 16, v51
	v_and_b32_e32 v51, 0xffff0000, v51
	v_rcp_f32_e32 v25, v20
	v_pk_fma_f32 v[20:21], v[18:19], v[50:51], v[28:29]
	v_pk_fma_f32 v[18:19], v[22:23], v[58:59], v[26:27]
	v_rcp_f32_e32 v26, v10
	v_mul_f32_e64 v10, v202, -v15
	v_mul_f32_e32 v10, 0x3fb8aa3b, v10
	v_exp_f32_e32 v10, v10
	v_lshlrev_b32_e32 v30, 16, v60
	v_and_b32_e32 v31, 0xffff0000, v60
	v_lshlrev_b32_e32 v32, 16, v61
	v_add_f32_e32 v10, 1.0, v10
	v_rcp_f32_e32 v15, v10
	v_mul_f32_e64 v10, v202, -v11
	v_mul_f32_e64 v11, v202, -v12
	v_mul_f32_e32 v10, 0x3fb8aa3b, v10
	v_mul_f32_e32 v11, 0x3fb8aa3b, v11
	v_exp_f32_e32 v10, v10
	v_exp_f32_e32 v11, v11
	v_mul_f32_e64 v12, v202, -v13
	v_mul_f32_e32 v12, 0x3fb8aa3b, v12
	v_add_f32_e32 v10, 1.0, v10
	v_add_f32_e32 v11, 1.0, v11
	v_rcp_f32_e32 v27, v10
	v_mul_f32_e64 v10, v202, -v16
	v_rcp_f32_e32 v16, v11
	v_mul_f32_e64 v11, v202, -v17
	v_mul_f32_e32 v10, 0x3fb8aa3b, v10
	v_mul_f32_e32 v11, 0x3fb8aa3b, v11
	v_exp_f32_e32 v10, v10
	v_exp_f32_e32 v11, v11
	v_exp_f32_e32 v12, v12
	v_and_b32_e32 v33, 0xffff0000, v61
	v_add_f32_e32 v10, 1.0, v10
	v_add_f32_e32 v11, 1.0, v11
	v_rcp_f32_e32 v10, v10
	v_rcp_f32_e32 v11, v11
	v_lshlrev_b32_e32 v60, 16, v52
	v_and_b32_e32 v61, 0xffff0000, v52
	v_lshlrev_b32_e32 v52, 16, v53
	v_and_b32_e32 v53, 0xffff0000, v53
	v_pk_fma_f32 v[24:25], v[24:25], v[52:53], v[32:33]
	v_pk_fma_f32 v[22:23], v[56:57], v[60:61], v[30:31]
	global_store_dwordx4 v[54:55], v[18:21], off offset:512 nt
	global_store_dwordx4 v[54:55], v[22:25], off offset:528 nt
	s_waitcnt vmcnt(6)
	v_lshlrev_b32_e32 v32, 16, v43
	v_lshlrev_b32_e32 v20, 16, v47
	v_and_b32_e32 v21, 0xffff0000, v47
	v_and_b32_e32 v33, 0xffff0000, v43
	v_add_f32_e32 v12, 1.0, v12
	v_rcp_f32_e32 v17, v12
	v_pk_fma_f32 v[12:13], v[10:11], v[32:33], v[20:21]
	v_rcp_f32_e32 v20, v2
	v_mul_f32_e64 v2, v202, -v7
	v_mul_f32_e32 v2, 0x3fb8aa3b, v2
	v_exp_f32_e32 v2, v2
	v_lshlrev_b32_e32 v18, 16, v46
	v_and_b32_e32 v19, 0xffff0000, v46
	v_lshlrev_b32_e32 v28, 16, v42
	v_add_f32_e32 v2, 1.0, v2
	v_rcp_f32_e32 v7, v2
	v_mul_f32_e64 v2, v202, -v3
	v_mul_f32_e64 v3, v202, -v4
	v_mul_f32_e32 v2, 0x3fb8aa3b, v2
	v_mul_f32_e32 v3, 0x3fb8aa3b, v3
	v_exp_f32_e32 v2, v2
	v_exp_f32_e32 v3, v3
	v_mul_f32_e64 v4, v202, -v5
	v_mul_f32_e32 v4, 0x3fb8aa3b, v4
	v_add_f32_e32 v2, 1.0, v2
	v_add_f32_e32 v3, 1.0, v3
	v_rcp_f32_e32 v21, v2
	v_mul_f32_e64 v2, v202, -v8
	v_rcp_f32_e32 v8, v3
	v_mul_f32_e64 v3, v202, -v9
	v_mul_f32_e32 v2, 0x3fb8aa3b, v2
	v_mul_f32_e32 v3, 0x3fb8aa3b, v3
	v_exp_f32_e32 v2, v2
	v_exp_f32_e32 v3, v3
	v_exp_f32_e32 v4, v4
	v_and_b32_e32 v29, 0xffff0000, v42
	v_add_f32_e32 v2, 1.0, v2
	v_add_f32_e32 v3, 1.0, v3
	v_rcp_f32_e32 v2, v2
	v_rcp_f32_e32 v3, v3
	v_add_f32_e32 v4, 1.0, v4
	v_rcp_f32_e32 v9, v4
	v_lshlrev_b32_e32 v22, 16, v48
	v_and_b32_e32 v23, 0xffff0000, v48
	v_lshlrev_b32_e32 v24, 16, v49
	v_and_b32_e32 v25, 0xffff0000, v49
	v_lshlrev_b32_e32 v30, 16, v44
	v_and_b32_e32 v31, 0xffff0000, v44
	v_lshlrev_b32_e32 v42, 16, v45
	v_and_b32_e32 v43, 0xffff0000, v45
	v_pk_fma_f32 v[10:11], v[14:15], v[28:29], v[18:19]
	v_lshl_add_u64 v[18:19], v[62:63], 2, s[52:53]
	v_pk_fma_f32 v[16:17], v[16:17], v[42:43], v[24:25]
	v_pk_fma_f32 v[14:15], v[26:27], v[30:31], v[22:23]
	global_store_dwordx4 v[18:19], v[10:13], off nt
	global_store_dwordx4 v[18:19], v[14:17], off offset:16 nt
	s_waitcnt vmcnt(6)
	v_lshlrev_b32_e32 v22, 16, v34
	v_lshlrev_b32_e32 v10, 16, v38
	v_and_b32_e32 v11, 0xffff0000, v38
	v_lshlrev_b32_e32 v12, 16, v39
	v_and_b32_e32 v13, 0xffff0000, v39
	v_and_b32_e32 v23, 0xffff0000, v34
	v_lshlrev_b32_e32 v26, 16, v35
	v_and_b32_e32 v27, 0xffff0000, v35
	v_lshlrev_b32_e32 v14, 16, v40
	v_and_b32_e32 v15, 0xffff0000, v40
	v_lshlrev_b32_e32 v16, 16, v41
	v_and_b32_e32 v17, 0xffff0000, v41
	v_lshlrev_b32_e32 v24, 16, v36
	v_and_b32_e32 v25, 0xffff0000, v36
	v_lshlrev_b32_e32 v28, 16, v37
	v_and_b32_e32 v29, 0xffff0000, v37
	v_pk_fma_f32 v[4:5], v[2:3], v[26:27], v[12:13]
	v_pk_fma_f32 v[2:3], v[6:7], v[22:23], v[10:11]
	v_pk_fma_f32 v[8:9], v[8:9], v[28:29], v[16:17]
	v_pk_fma_f32 v[6:7], v[20:21], v[24:25], v[14:15]
	global_store_dwordx4 v[18:19], v[2:5], off offset:512 nt
	global_store_dwordx4 v[18:19], v[6:9], off offset:528 nt
	s_cbranch_vccnz .LBB0_1799
	s_andn2_b64 vcc, exec, s[0:1]
	s_cbranch_vccnz .LBB0_1798
	s_barrier
	s_branch .LBB0_1798
